# v15 + qk_prep: the 16 loop-invariant gain-vector loads hoisted out of the item loop (were 14 exposed L2 round trips per item)
# speedup vs baseline: 1.0031x; 1.0031x over previous
.LBB0_970:
	s_lshl_b32 s7, s7, 9
	v_and_b32_e32 v2, 63, v1
	s_add_i32 s7, s7, s6
	v_or_b32_e32 v0, s7, v2
	v_ashrrev_i32_e32 v49, 2, v0
	v_cmp_gt_i32_e32 vcc, s95, v49
	s_and_saveexec_b64 s[6:7], vcc
	s_cbranch_execz .LBB0_973
	s_load_dwordx4 s[16:19], s[2:3], 0x78
	v_readlane_b32 s2, v255, 20
	v_and_b32_e32 v4, 3, v1
	v_lshlrev_b32_e32 v1, 3, v2
	v_readlane_b32 s3, v255, 21
	s_waitcnt lgkmcnt(0)
	s_add_u32 s8, s18, s2
	v_and_b32_e32 v1, 8, v1
	s_addc_u32 s9, s19, s3
	v_cvt_f32_ubyte0_e32 v2, v1
	s_add_u32 s10, s16, s2
	v_mul_f32_e32 v3, 0xbf549a78, v2
	s_mov_b32 s13, 0xc2fc0000
	s_addc_u32 s11, s17, s3
	v_cmp_gt_f32_e64 s[2:3], s13, v3
	v_mov_b32_e32 v5, 0x42800000
	v_not_b32_e32 v6, 63
	v_cndmask_b32_e64 v3, 0, v5, s[2:3]
	v_fmac_f32_e32 v3, 0xbf549a78, v2
	v_exp_f32_e32 v2, v3
	v_cndmask_b32_e64 v3, 0, v6, s[2:3]
	v_lshlrev_b32_e32 v96, 4, v4
	v_mov_b32_e32 v7, v97
	v_ldexp_f32 v2, v2, v3
	v_cvt_f64_f32_e32 v[16:17], v2
	v_or_b32_e32 v2, 1, v1
	v_cvt_f32_ubyte0_e32 v2, v2
	v_mul_f32_e32 v3, 0xbf549a78, v2
	v_cmp_gt_f32_e64 s[2:3], s13, v3
	v_mov_b32_e32 v9, v97
	v_cmp_gt_u32_e32 vcc, 2, v4
	v_cndmask_b32_e64 v3, 0, v5, s[2:3]
	v_fmac_f32_e32 v3, 0xbf549a78, v2
	v_exp_f32_e32 v2, v3
	v_cndmask_b32_e64 v3, 0, v6, s[2:3]
	s_lshl_b32 s12, s12, 7
	v_ldexp_f32 v2, v2, v3
	v_cvt_f64_f32_e32 v[18:19], v2
	v_or_b32_e32 v2, 2, v1
	v_cvt_f32_ubyte0_e32 v2, v2
	v_mul_f32_e32 v3, 0xbf549a78, v2
	v_cmp_gt_f32_e64 s[2:3], s13, v3
	s_nop 1
	v_cndmask_b32_e64 v3, 0, v5, s[2:3]
	v_fmac_f32_e32 v3, 0xbf549a78, v2
	v_exp_f32_e32 v2, v3
	v_cndmask_b32_e64 v3, 0, v6, s[2:3]
	v_ldexp_f32 v2, v2, v3
	v_cvt_f64_f32_e32 v[20:21], v2
	v_or_b32_e32 v2, 3, v1
	v_cvt_f32_ubyte0_e32 v2, v2
	v_mul_f32_e32 v3, 0xbf549a78, v2
	v_cmp_gt_f32_e64 s[2:3], s13, v3
	s_nop 1
	v_cndmask_b32_e64 v3, 0, v5, s[2:3]
	v_fmac_f32_e32 v3, 0xbf549a78, v2
	v_exp_f32_e32 v2, v3
	v_cndmask_b32_e64 v3, 0, v6, s[2:3]
	v_ldexp_f32 v2, v2, v3
	v_cvt_f64_f32_e32 v[22:23], v2
	v_or_b32_e32 v2, 4, v1
	v_cvt_f32_ubyte0_e32 v2, v2
	v_mul_f32_e32 v3, 0xbf549a78, v2
	v_cmp_gt_f32_e64 s[2:3], s13, v3
	s_nop 1
	v_cndmask_b32_e64 v3, 0, v5, s[2:3]
	v_fmac_f32_e32 v3, 0xbf549a78, v2
	v_exp_f32_e32 v2, v3
	v_cndmask_b32_e64 v3, 0, v6, s[2:3]
	v_ldexp_f32 v2, v2, v3
	v_cvt_f64_f32_e32 v[24:25], v2
	v_or_b32_e32 v2, 5, v1
	v_cvt_f32_ubyte0_e32 v2, v2
	v_mul_f32_e32 v3, 0xbf549a78, v2
	v_cmp_gt_f32_e64 s[2:3], s13, v3
	s_nop 1
	v_cndmask_b32_e64 v3, 0, v5, s[2:3]
	v_fmac_f32_e32 v3, 0xbf549a78, v2
	v_exp_f32_e32 v2, v3
	v_cndmask_b32_e64 v3, 0, v6, s[2:3]
	v_ldexp_f32 v2, v2, v3
	v_cvt_f64_f32_e32 v[26:27], v2
	v_or_b32_e32 v2, 6, v1
	v_cvt_f32_ubyte0_e32 v2, v2
	v_mul_f32_e32 v3, 0xbf549a78, v2
	v_cmp_gt_f32_e64 s[2:3], s13, v3
	v_or_b32_e32 v1, 7, v1
	v_cvt_f32_ubyte0_e32 v1, v1
	v_cndmask_b32_e64 v3, 0, v5, s[2:3]
	v_fmac_f32_e32 v3, 0xbf549a78, v2
	v_exp_f32_e32 v2, v3
	v_cndmask_b32_e64 v3, 0, v6, s[2:3]
	v_ldexp_f32 v2, v2, v3
	v_cvt_f64_f32_e32 v[28:29], v2
	v_mul_f32_e32 v2, 0xbf549a78, v1
	v_cmp_gt_f32_e64 s[2:3], s13, v2
	s_nop 1
	v_cndmask_b32_e64 v2, 0, v5, s[2:3]
	v_fmac_f32_e32 v2, 0xbf549a78, v1
	v_exp_f32_e32 v1, v2
	v_cndmask_b32_e64 v2, 0, v6, s[2:3]
	s_mov_b64 s[2:3], 0x15a00000
	v_lshlrev_b32_e32 v6, 5, v4
	v_ldexp_f32 v1, v1, v2
	v_lshl_add_u64 v[2:3], s[4:5], 0, v[96:97]
	v_lshl_add_u64 v[32:33], v[2:3], 0, s[2:3]
	s_mov_b64 s[2:3], 0x12200000
	v_lshl_add_u64 v[38:39], v[2:3], 0, s[2:3]
	v_bfe_u32 v2, v0, 2, 3
	v_mul_u32_u24_e32 v0, 0x60, v2
	v_cvt_f64_f32_e32 v[30:31], v1
	v_lshlrev_b32_e32 v0, 1, v0
	v_mov_b32_e32 v1, v97
	v_lshl_add_u64 v[0:1], s[4:5], 0, v[0:1]
	v_lshl_add_u64 v[0:1], v[0:1], 0, v[96:97]
	s_mov_b64 s[2:3], 0xea00000
	v_lshl_add_u64 v[44:45], v[0:1], 0, s[2:3]
	v_lshlrev_b32_e32 v0, 7, v2
	v_mov_b32_e32 v1, v97
	v_lshl_add_u64 v[0:1], s[4:5], 0, v[0:1]
	v_xor_b32_e32 v8, 64, v6
	v_lshl_add_u64 v[0:1], v[0:1], 0, v[96:97]
	s_mov_b64 s[2:3], 0x10200000
	v_lshl_add_u64 v[34:35], s[10:11], 0, v[6:7]
	v_lshl_add_u64 v[36:37], s[10:11], 0, v[8:9]
	v_lshl_add_u64 v[40:41], s[8:9], 0, v[6:7]
	v_lshl_add_u64 v[42:43], s[8:9], 0, v[8:9]
	v_lshl_add_u64 v[46:47], v[0:1], 0, s[2:3]
	v_lshlrev_b32_e32 v48, 14, v2
	s_mov_b64 s[8:9], 0
	v_lshlrev_b32_e32 v96, 4, v4
	global_load_dwordx4 v[110:113], v[34:35], off offset:16
	global_load_dwordx4 v[114:117], v[34:35], off
	global_load_dwordx4 v[118:121], v[34:35], off offset:144
	global_load_dwordx4 v[122:125], v[34:35], off offset:128
	global_load_dwordx4 v[126:129], v[34:35], off offset:272
	global_load_dwordx4 v[130:133], v[34:35], off offset:256
	global_load_dwordx4 v[134:137], v[36:37], off offset:272
	global_load_dwordx4 v[138:141], v[36:37], off offset:256
	global_load_dwordx4 v[142:145], v[40:41], off offset:16
	global_load_dwordx4 v[146:149], v[40:41], off
	global_load_dwordx4 v[150:153], v[40:41], off offset:144
	global_load_dwordx4 v[154:157], v[40:41], off offset:128
	global_load_dwordx4 v[158:161], v[40:41], off offset:272
	global_load_dwordx4 v[162:165], v[40:41], off offset:256
	global_load_dwordx4 v[166:169], v[42:43], off offset:272
	global_load_dwordx4 v[170:173], v[42:43], off offset:256
	s_waitcnt vmcnt(0)
.LBB0_972:
	v_ashrrev_i32_e32 v74, 3, v49
	v_mad_i64_i32 v[0:1], s[2:3], v74, s84, v[44:45]
	global_load_dwordx4 v[66:69], v[0:1], off
	global_load_dwordx4 v[70:73], v[0:1], off offset:64
	global_load_dwordx4 v[12:15], v[0:1], off offset:128
	v_cvt_f64_i32_e32 v[64:65], v74
	v_mul_f64 v[50:51], v[16:17], v[64:65]
	v_mul_f64 v[52:53], v[50:51], s[58:59]
	v_rndne_f64_e32 v[52:53], v[52:53]
	v_fma_f64 v[50:51], v[50:51], s[58:59], -v[52:53]
	v_mul_f64 v[52:53], v[18:19], v[64:65]
	v_mul_f64 v[54:55], v[52:53], s[58:59]
	v_rndne_f64_e32 v[54:55], v[54:55]
	v_fma_f64 v[52:53], v[52:53], s[58:59], -v[54:55]
	v_mul_f64 v[54:55], v[20:21], v[64:65]
	v_mul_f64 v[56:57], v[54:55], s[58:59]
	v_rndne_f64_e32 v[56:57], v[56:57]
	v_fma_f64 v[54:55], v[54:55], s[58:59], -v[56:57]
	v_mul_f64 v[56:57], v[22:23], v[64:65]
	v_mul_f64 v[58:59], v[56:57], s[58:59]
	v_rndne_f64_e32 v[58:59], v[58:59]
	v_fma_f64 v[56:57], v[56:57], s[58:59], -v[58:59]
	v_mul_f64 v[58:59], v[24:25], v[64:65]
	v_mul_f64 v[60:61], v[58:59], s[58:59]
	v_rndne_f64_e32 v[60:61], v[60:61]
	v_fma_f64 v[58:59], v[58:59], s[58:59], -v[60:61]
	v_mul_f64 v[60:61], v[26:27], v[64:65]
	v_mul_f64 v[62:63], v[60:61], s[58:59]
	v_rndne_f64_e32 v[62:63], v[62:63]
	v_fma_f64 v[60:61], v[60:61], s[58:59], -v[62:63]
	v_mul_f64 v[62:63], v[28:29], v[64:65]
	v_ashrrev_i32_e32 v75, 31, v74
	v_mul_f64 v[76:77], v[62:63], s[58:59]
	v_lshlrev_b64 v[0:1], 10, v[74:75]
	v_rndne_f64_e32 v[76:77], v[76:77]
	v_mul_f64 v[64:65], v[30:31], v[64:65]
	v_lshl_add_u64 v[0:1], v[46:47], 0, v[0:1]
	v_fma_f64 v[62:63], v[62:63], s[58:59], -v[76:77]
	v_mul_f64 v[76:77], v[64:65], s[58:59]
	global_load_dwordx4 v[8:11], v[0:1], off
	global_load_dwordx4 v[4:7], v[0:1], off offset:64
	v_mov_b64_e32 v[0:1], s[4:5]
	v_rndne_f64_e32 v[76:77], v[76:77]
	v_mad_i64_i32 v[0:1], s[2:3], v74, s77, v[0:1]
	v_fma_f64 v[64:65], v[64:65], s[58:59], -v[76:77]
	v_add_u32_e32 v88, v48, v74
	v_lshl_add_u64 v[0:1], v[0:1], 0, v[96:97]
	s_mov_b32 s2, 0xc200000
	v_add_co_u32_e64 v0, s[2:3], s2, v0
	v_cvt_f32_f64_e32 v51, v[50:51]
	s_nop 0
	v_addc_co_u32_e64 v1, s[2:3], 0, v1, s[2:3]
	global_load_dwordx4 v[0:3], v[0:1], off offset:2304
	v_cos_f32_e32 v50, v51
	v_sin_f32_e32 v51, v51
	v_cvt_f32_f64_e32 v53, v[52:53]
	v_cos_f32_e32 v52, v53
	v_sin_f32_e32 v53, v53
	v_cvt_f32_f64_e32 v55, v[54:55]
	v_cos_f32_e32 v54, v55
	v_sin_f32_e32 v55, v55
	v_cvt_f32_f64_e32 v57, v[56:57]
	v_cvt_f32_f64_e32 v59, v[58:59]
	v_cos_f32_e32 v56, v57
	v_sin_f32_e32 v57, v57
	v_cos_f32_e32 v58, v59
	v_sin_f32_e32 v59, v59
	v_cvt_f32_f64_e32 v61, v[60:61]
	v_cos_f32_e32 v60, v61
	v_sin_f32_e32 v61, v61
	v_cvt_f32_f64_e32 v63, v[62:63]
	v_cos_f32_e32 v62, v63
	v_sin_f32_e32 v63, v63
	v_cvt_f32_f64_e32 v65, v[64:65]
	v_cos_f32_e32 v64, v65
	v_sin_f32_e32 v65, v65
	v_add_u32_e32 v49, s12, v49
	s_waitcnt vmcnt(5)
	v_and_b32_e32 v81, 0xffff0000, v67
	v_and_b32_e32 v83, 0xffff0000, v66
	v_and_b32_e32 v82, 0xffff0000, v68
	v_lshlrev_b32_e32 v80, 16, v67
	v_mul_f32_e32 v74, v81, v81
	v_lshlrev_b32_e32 v85, 16, v66
	v_lshlrev_b32_e32 v84, 16, v68
	v_pk_mul_f32 v[66:67], v[82:83], v[82:83]
	s_waitcnt vmcnt(4)
	v_and_b32_e32 v79, 0xffff0000, v70
	v_and_b32_e32 v77, 0xffff0000, v71
	v_pk_fma_f32 v[74:75], v[80:81], v[80:81], v[74:75] op_sel_hi:[1,1,0]
	v_pk_fma_f32 v[66:67], v[84:85], v[84:85], v[66:67]
	v_lshlrev_b32_e32 v78, 16, v70
	v_lshlrev_b32_e32 v76, 16, v71
	s_waitcnt vmcnt(3)
	v_lshlrev_b32_e32 v90, 16, v13
	v_and_b32_e32 v91, 0xffff0000, v13
	v_mul_f32_e32 v98, v79, v79
	v_mul_f32_e32 v100, v77, v77
	v_pk_add_f32 v[74:75], v[66:67], v[74:75] op_sel:[1,0] op_sel_hi:[0,1]
	v_lshlrev_b32_e32 v92, 16, v69
	v_and_b32_e32 v93, 0xffff0000, v69
	v_mul_f32_e32 v95, v90, v90
	v_mul_f32_e32 v102, v91, v91
	v_and_b32_e32 v69, 0xffff0000, v12
	v_and_b32_e32 v68, 0xffff0000, v72
	v_pk_fma_f32 v[98:99], v[78:79], v[78:79], v[98:99] op_sel_hi:[1,1,0]
	v_pk_fma_f32 v[100:101], v[76:77], v[76:77], v[100:101] op_sel_hi:[1,1,0]
	v_pk_add_f32 v[86:87], v[66:67], v[74:75]
	v_lshlrev_b32_e32 v71, 16, v12
	v_lshlrev_b32_e32 v70, 16, v72
	v_pk_mul_f32 v[74:75], v[68:69], v[68:69]
	v_mov_b32_e32 v99, v95
	v_mov_b32_e32 v101, v102
	v_pk_fma_f32 v[74:75], v[70:71], v[70:71], v[74:75]
	v_pk_add_f32 v[98:99], v[98:99], v[100:101]
	v_pk_mov_b32 v[100:101], v[72:73], v[14:15] op_sel:[1,0]
	v_pk_add_f32 v[98:99], v[74:75], v[98:99]
	v_lshlrev_b32_e32 v74, 16, v73
	v_and_b32_e32 v73, 0xffff0000, v101
	v_and_b32_e32 v72, 0xffff0000, v100
	v_lshlrev_b32_e32 v67, 16, v15
	v_lshlrev_b32_e32 v75, 16, v14
	v_pk_mul_f32 v[100:101], v[72:73], v[72:73]
	v_mul_f32_e32 v66, v92, v92
	v_mul_f32_e32 v94, v93, v93
	v_pk_fma_f32 v[100:101], v[74:75], v[74:75], v[100:101]
	v_mov_b32_e32 v95, v67
	v_and_b32_e32 v89, 0xffff0000, v15
	v_pk_add_f32 v[98:99], v[100:101], v[98:99]
	v_pk_add_f32 v[94:95], v[66:67], v[94:95]
	v_pk_mul_f32 v[100:101], v[66:67], v[66:67]
	v_mul_f32_e32 v87, v89, v89
	v_mov_b32_e32 v95, v101
	v_pk_add_f32 v[86:87], v[94:95], v[86:87]
	s_nop 0
	v_pk_add_f32 v[86:87], v[86:87], v[98:99]
	s_nop 0
	v_add_f32_e32 v66, v86, v87
	v_mov_b32_e32 v86, v248
	s_nop 0
	v_lshlrev_b32_e32 v86, 2, v86
	v_xor_b32_e32 v86, 4, v86
	ds_bpermute_b32 v86, v86, v66
	s_waitcnt lgkmcnt(0)
	v_add_f32_e32 v66, v66, v86
	v_mov_b32_e32 v86, v248
	v_mov_b64_e32 v[98:99], v[110:111]
	v_mov_b64_e32 v[100:101], v[112:113]
	v_mov_b64_e32 v[102:103], v[114:115]
	v_mov_b64_e32 v[104:105], v[116:117]
	v_lshlrev_b32_e32 v86, 2, v86
	v_xor_b32_e32 v86, 8, v86
	ds_bpermute_b32 v86, v86, v66
	s_waitcnt lgkmcnt(0)
	v_add_f32_e32 v66, v66, v86
	v_fmamk_f32 v66, v66, 0x3c2aaaab, v249
	v_rsq_f32_e32 v66, v66
	v_mad_i64_i32 v[86:87], s[2:3], v88, s63, v[32:33]
	v_mul_f32_e32 v106, 0x3e16c740, v66
	v_mul_f32_e32 v66, v106, v85
	v_mul_f32_e32 v83, v106, v83
	v_mul_f32_e32 v68, v106, v68
	s_waitcnt vmcnt(0)
	v_mul_f32_e32 v66, v102, v66
	v_mul_f32_e32 v83, v103, v83
	v_cvt_pk_bf16_f32 v102, v66, v83
	v_mul_f32_e32 v66, v106, v80
	v_mul_f32_e32 v80, v106, v81
	v_mul_f32_e32 v66, v104, v66
	v_mul_f32_e32 v80, v105, v80
	v_cvt_pk_bf16_f32 v103, v66, v80
	v_mul_f32_e32 v66, v106, v84
	v_mul_f32_e32 v80, v106, v82
	v_mul_f32_e32 v66, v98, v66
	v_mul_f32_e32 v80, v99, v80
	v_cvt_pk_bf16_f32 v104, v66, v80
	v_mul_f32_e32 v66, v106, v92
	v_mul_f32_e32 v80, v106, v93
	v_mul_f32_e32 v66, v100, v66
	v_mul_f32_e32 v80, v101, v80
	v_cvt_pk_bf16_f32 v105, v66, v80
	global_store_dwordx4 v[86:87], v[102:105], off
	v_mov_b64_e32 v[80:81], v[118:119]
	v_mov_b64_e32 v[82:83], v[120:121]
	v_mov_b64_e32 v[92:93], v[122:123]
	v_mov_b64_e32 v[94:95], v[124:125]
	v_mul_f32_e32 v66, v106, v78
	v_mul_f32_e32 v78, v106, v79
	s_waitcnt vmcnt(1)
	v_mul_f32_e32 v68, v68, v81
	s_waitcnt vmcnt(0)
	v_mul_f32_e32 v66, v92, v66
	v_mul_f32_e32 v78, v93, v78
	v_cvt_pk_bf16_f32 v78, v66, v78
	v_mul_f32_e32 v66, v106, v76
	v_mul_f32_e32 v66, v94, v66
	v_mul_f32_e32 v76, v106, v77
	v_mul_f32_e32 v76, v95, v76
	v_cvt_pk_bf16_f32 v79, v66, v76
	v_mul_f32_e32 v66, v106, v70
	v_mul_f32_e32 v66, v66, v80
	v_cvt_pk_bf16_f32 v80, v66, v68
	v_mul_f32_e32 v66, v106, v74
	v_mul_f32_e32 v66, v66, v82
	v_mul_f32_e32 v68, v106, v72
	v_mul_f32_e32 v68, v68, v83
	v_cvt_pk_bf16_f32 v81, v66, v68
	v_mov_b32_e32 v66, v248
	global_store_dwordx4 v[86:87], v[78:81], off offset:64
	v_mul_f32_e32 v68, v106, v69
	v_lshlrev_b32_e32 v66, 2, v66
	v_xor_b32_e32 v66, 8, v66
	ds_bpermute_b32 v84, v66, v12
	v_mov_b32_e32 v12, v248
	v_mul_f32_e32 v69, v106, v90
	v_lshlrev_b32_e32 v12, 2, v12
	v_xor_b32_e32 v12, 8, v12
	ds_bpermute_b32 v85, v12, v13
	v_mov_b32_e32 v12, v248
	v_mul_f32_e32 v66, v106, v71
	v_lshlrev_b32_e32 v12, 2, v12
	v_xor_b32_e32 v12, 8, v12
	ds_bpermute_b32 v98, v12, v14
	v_mov_b32_e32 v12, v248
	s_nop 0
	v_lshlrev_b32_e32 v12, 2, v12
	v_xor_b32_e32 v12, 8, v12
	ds_bpermute_b32 v99, v12, v15
	v_mov_b64_e32 v[12:13], v[126:127]
	v_mov_b64_e32 v[14:15], v[128:129]
	v_mov_b64_e32 v[76:77], v[130:131]
	v_mov_b64_e32 v[78:79], v[132:133]
	v_mov_b64_e32 v[80:81], v[134:135]
	v_mov_b64_e32 v[82:83], v[136:137]
	v_mov_b64_e32 v[92:93], v[138:139]
	v_mov_b64_e32 v[94:95], v[140:141]
	s_waitcnt vmcnt(2)
	v_mul_f32_e32 v70, v69, v78
	v_mul_f32_e32 v69, v106, v91
	v_mul_f32_e32 v72, v69, v79
	v_mul_f32_e32 v69, v106, v75
	v_mul_f32_e32 v12, v69, v12
	v_mul_f32_e32 v69, v106, v73
	v_mul_f32_e32 v74, v69, v13
	v_mul_f32_e32 v13, v106, v67
	s_waitcnt lgkmcnt(2)
	v_lshlrev_b32_e32 v67, 16, v85
	v_mul_f32_e32 v67, v106, v67
	s_waitcnt vmcnt(0)
	v_mul_f32_e32 v71, v67, v94
	v_and_b32_e32 v67, 0xffff0000, v85
	v_mul_f32_e32 v67, v106, v67
	v_mul_f32_e32 v73, v67, v95
	s_waitcnt lgkmcnt(1)
	v_lshlrev_b32_e32 v67, 16, v98
	v_mul_f32_e32 v67, v106, v67
	v_mul_f32_e32 v75, v67, v80
	v_and_b32_e32 v67, 0xffff0000, v98
	v_mul_f32_e32 v67, v106, v67
	v_mul_f32_e32 v68, v68, v77
	v_mul_f32_e32 v14, v13, v14
	v_mul_f32_e32 v13, v106, v89
	v_mul_f32_e32 v77, v67, v81
	s_waitcnt lgkmcnt(0)
	v_lshlrev_b32_e32 v67, 16, v99
	v_mul_f32_e32 v66, v66, v76
	v_mul_f32_e32 v76, v13, v15
	v_lshlrev_b32_e32 v13, 16, v84
	v_mul_f32_e32 v67, v106, v67
	v_mul_f32_e32 v13, v106, v13
	v_and_b32_e32 v15, 0xffff0000, v84
	v_mul_f32_e32 v78, v67, v82
	v_and_b32_e32 v67, 0xffff0000, v99
	v_mul_f32_e32 v13, v13, v92
	v_mul_f32_e32 v15, v106, v15
	v_mul_f32_e32 v67, v106, v67
	v_mul_f32_e32 v15, v15, v93
	v_mul_f32_e32 v79, v67, v83
	v_cndmask_b32_e64 v67, v13, -v13, vcc
	v_pk_mul_f32 v[66:67], v[50:51], v[66:67]
	v_cndmask_b32_e64 v69, v15, -v15, vcc
	v_add_f32_e32 v80, v66, v67
	v_pk_mul_f32 v[66:67], v[52:53], v[68:69]
	v_cndmask_b32_e64 v71, v71, -v71, vcc
	v_add_f32_e32 v68, v66, v67
	v_pk_mul_f32 v[66:67], v[54:55], v[70:71]
	v_cndmask_b32_e64 v73, v73, -v73, vcc
	v_cndmask_b32_e64 v13, v75, -v75, vcc
	v_add_f32_e32 v69, v66, v67
	v_pk_mul_f32 v[66:67], v[56:57], v[72:73]
	v_pk_mul_f32 v[12:13], v[58:59], v[12:13]
	v_cndmask_b32_e64 v75, v77, -v77, vcc
	v_add_f32_e32 v66, v66, v67
	v_add_f32_e32 v67, v12, v13
	v_pk_mul_f32 v[12:13], v[60:61], v[74:75]
	v_cndmask_b32_e64 v15, v78, -v78, vcc
	v_add_f32_e32 v70, v12, v13
	v_pk_mul_f32 v[12:13], v[62:63], v[14:15]
	v_cndmask_b32_e64 v77, v79, -v79, vcc
	v_add_f32_e32 v15, v12, v13
	v_pk_mul_f32 v[12:13], v[64:65], v[76:77]
	v_and_b32_e32 v77, 0xffff0000, v9
	v_add_f32_e32 v71, v12, v13
	v_cvt_pk_bf16_f32 v12, v80, v68
	v_cvt_pk_bf16_f32 v13, v69, v66
	v_cvt_pk_bf16_f32 v14, v67, v70
	v_cvt_pk_bf16_f32 v15, v15, v71
	v_and_b32_e32 v71, 0xffff0000, v4
	global_store_dwordx4 v[86:87], v[12:15], off offset:128
	v_and_b32_e32 v73, 0xffff0000, v8
	v_and_b32_e32 v72, 0xffff0000, v10
	v_lshlrev_b32_e32 v70, 16, v4
	v_lshlrev_b32_e32 v81, 16, v1
	v_mul_f32_e32 v14, v71, v71
	v_lshlrev_b32_e32 v76, 16, v9
	v_mul_f32_e32 v12, v77, v77
	v_lshlrev_b32_e32 v75, 16, v8
	v_lshlrev_b32_e32 v74, 16, v10
	v_pk_mul_f32 v[8:9], v[72:73], v[72:73]
	v_and_b32_e32 v69, 0xffff0000, v5
	v_mul_f32_e32 v66, v81, v81
	v_pk_fma_f32 v[14:15], v[70:71], v[70:71], v[14:15] op_sel_hi:[1,1,0]
	v_pk_fma_f32 v[12:13], v[76:77], v[76:77], v[12:13] op_sel_hi:[1,1,0]
	v_pk_fma_f32 v[8:9], v[74:75], v[74:75], v[8:9]
	v_lshlrev_b32_e32 v68, 16, v5
	v_and_b32_e32 v82, 0xffff0000, v1
	v_mov_b32_e32 v15, v66
	v_mul_f32_e32 v66, v69, v69
	v_pk_add_f32 v[12:13], v[8:9], v[12:13] op_sel:[1,0] op_sel_hi:[0,1]
	v_lshlrev_b32_e32 v84, 16, v11
	v_and_b32_e32 v83, 0xffff0000, v11
	v_mul_f32_e32 v85, v82, v82
	v_and_b32_e32 v11, 0xffff0000, v0
	v_and_b32_e32 v10, 0xffff0000, v6
	v_pk_fma_f32 v[66:67], v[68:69], v[68:69], v[66:67] op_sel_hi:[1,1,0]
	v_pk_add_f32 v[78:79], v[8:9], v[12:13]
	v_lshlrev_b32_e32 v13, 16, v0
	v_lshlrev_b32_e32 v12, 16, v6
	v_pk_mul_f32 v[4:5], v[10:11], v[10:11]
	v_mov_b32_e32 v67, v85
	v_pk_fma_f32 v[4:5], v[12:13], v[12:13], v[4:5]
	v_pk_add_f32 v[14:15], v[14:15], v[66:67]
	v_lshlrev_b32_e32 v9, 16, v3
	v_pk_add_f32 v[4:5], v[4:5], v[14:15]
	v_pk_mov_b32 v[14:15], v[6:7], v[2:3] op_sel:[1,0]
	v_lshlrev_b32_e32 v67, 16, v2
	v_and_b32_e32 v15, 0xffff0000, v15
	v_and_b32_e32 v14, 0xffff0000, v14
	v_lshlrev_b32_e32 v66, 16, v7
	v_pk_mul_f32 v[6:7], v[14:15], v[14:15]
	v_mul_f32_e32 v8, v84, v84
	v_mul_f32_e32 v86, v83, v83
	v_pk_fma_f32 v[6:7], v[66:67], v[66:67], v[6:7]
	v_mov_b32_e32 v87, v9
	v_and_b32_e32 v80, 0xffff0000, v3
	v_pk_add_f32 v[4:5], v[6:7], v[4:5]
	v_pk_add_f32 v[6:7], v[8:9], v[86:87]
	v_pk_mul_f32 v[86:87], v[8:9], v[8:9]
	v_mul_f32_e32 v79, v80, v80
	v_mov_b32_e32 v7, v87
	v_pk_add_f32 v[6:7], v[6:7], v[78:79]
	v_mad_i64_i32 v[78:79], s[2:3], v88, s63, v[38:39]
	v_pk_add_f32 v[4:5], v[6:7], v[4:5]
	s_mov_b32 s2, 0x1ffff
	v_add_f32_e32 v4, v4, v5
	v_mov_b32_e32 v5, v248
	v_cmp_lt_i32_e64 s[2:3], s2, v49
	v_lshlrev_b32_e32 v5, 2, v5
	v_xor_b32_e32 v5, 4, v5
	ds_bpermute_b32 v5, v5, v4
	s_or_b64 s[8:9], s[2:3], s[8:9]
	s_waitcnt lgkmcnt(0)
	v_add_f32_e32 v4, v4, v5
	v_mov_b32_e32 v5, v248
	s_nop 0
	v_lshlrev_b32_e32 v5, 2, v5
	v_xor_b32_e32 v5, 8, v5
	ds_bpermute_b32 v5, v5, v4
	s_waitcnt lgkmcnt(0)
	v_add_f32_e32 v4, v4, v5
	v_fmamk_f32 v4, v4, 0x3c2aaaab, v249
	v_rsq_f32_e32 v8, v4
	v_mov_b64_e32 v[4:5], v[142:143]
	v_mov_b64_e32 v[6:7], v[144:145]
	v_mov_b64_e32 v[86:87], v[146:147]
	v_mov_b64_e32 v[88:89], v[148:149]
	v_mul_f32_e32 v73, v8, v73
	v_mul_f32_e32 v75, v8, v75
	v_mul_f32_e32 v72, v8, v72
	v_mul_f32_e32 v70, v8, v70
	v_mul_f32_e32 v71, v8, v71
	v_mul_f32_e32 v12, v8, v12
	v_mul_f32_e32 v68, v8, v68
	v_mul_f32_e32 v69, v8, v69
	v_mul_f32_e32 v10, v8, v10
	s_waitcnt vmcnt(1)
	v_mul_f32_e32 v5, v5, v72
	s_waitcnt vmcnt(0)
	v_mul_f32_e32 v73, v87, v73
	v_mul_f32_e32 v75, v86, v75
	v_cvt_pk_bf16_f32 v86, v75, v73
	v_mul_f32_e32 v73, v8, v76
	v_mul_f32_e32 v73, v88, v73
	v_mul_f32_e32 v75, v8, v77
	v_mul_f32_e32 v75, v89, v75
	v_cvt_pk_bf16_f32 v87, v73, v75
	v_mul_f32_e32 v73, v8, v74
	v_mul_f32_e32 v4, v4, v73
	v_cvt_pk_bf16_f32 v88, v4, v5
	v_mul_f32_e32 v4, v8, v84
	v_mul_f32_e32 v5, v8, v83
	v_mul_f32_e32 v4, v6, v4
	v_mul_f32_e32 v5, v7, v5
	v_cvt_pk_bf16_f32 v89, v4, v5
	global_store_dwordx4 v[78:79], v[86:89], off
	v_mov_b64_e32 v[4:5], v[150:151]
	v_mov_b64_e32 v[6:7], v[152:153]
	v_mov_b64_e32 v[72:73], v[154:155]
	v_mov_b64_e32 v[74:75], v[156:157]
	s_waitcnt vmcnt(1)
	v_mul_f32_e32 v4, v12, v4
	s_waitcnt vmcnt(0)
	v_mul_f32_e32 v70, v70, v72
	v_mul_f32_e32 v71, v71, v73
	v_cvt_pk_bf16_f32 v70, v70, v71
	v_mul_f32_e32 v68, v68, v74
	v_mul_f32_e32 v69, v69, v75
	v_cvt_pk_bf16_f32 v71, v68, v69
	v_mul_f32_e32 v5, v10, v5
	v_cvt_pk_bf16_f32 v72, v4, v5
	v_mul_f32_e32 v4, v8, v66
	v_mul_f32_e32 v4, v4, v6
	v_mul_f32_e32 v5, v8, v14
	v_mul_f32_e32 v5, v5, v7
	v_cvt_pk_bf16_f32 v73, v4, v5
	v_mov_b32_e32 v4, v248
	global_store_dwordx4 v[78:79], v[70:73], off offset:64
	v_mul_f32_e32 v10, v8, v13
	v_lshlrev_b32_e32 v4, 2, v4
	v_xor_b32_e32 v4, 8, v4
	ds_bpermute_b32 v76, v4, v0
	v_mov_b32_e32 v0, v248
	s_nop 0
	v_lshlrev_b32_e32 v0, 2, v0
	v_xor_b32_e32 v0, 8, v0
	ds_bpermute_b32 v77, v0, v1
	v_mov_b32_e32 v0, v248
	s_nop 0
	v_lshlrev_b32_e32 v0, 2, v0
	v_xor_b32_e32 v0, 8, v0
	ds_bpermute_b32 v83, v0, v2
	v_mov_b32_e32 v0, v248
	s_nop 0
	v_lshlrev_b32_e32 v0, 2, v0
	v_xor_b32_e32 v0, 8, v0
	ds_bpermute_b32 v84, v0, v3
	v_mov_b64_e32 v[0:1], v[158:159]
	v_mov_b64_e32 v[2:3], v[160:161]
	v_mov_b64_e32 v[4:5], v[162:163]
	v_mov_b64_e32 v[6:7], v[164:165]
	v_mov_b64_e32 v[68:69], v[166:167]
	v_mov_b64_e32 v[70:71], v[168:169]
	v_mov_b64_e32 v[72:73], v[170:171]
	v_mov_b64_e32 v[74:75], v[172:173]
	s_waitcnt vmcnt(2)
	v_mul_f32_e32 v4, v10, v4
	v_mul_f32_e32 v10, v8, v11
	v_mul_f32_e32 v10, v10, v5
	v_mul_f32_e32 v5, v8, v81
	v_mul_f32_e32 v6, v5, v6
	v_mul_f32_e32 v5, v8, v82
	v_mul_f32_e32 v12, v5, v7
	v_mul_f32_e32 v5, v8, v67
	v_mul_f32_e32 v0, v5, v0
	v_mul_f32_e32 v5, v8, v15
	v_mul_f32_e32 v14, v5, v1
	s_waitcnt lgkmcnt(2)
	v_lshlrev_b32_e32 v5, 16, v77
	v_mul_f32_e32 v5, v8, v5
	s_waitcnt vmcnt(0)
	v_mul_f32_e32 v7, v5, v74
	v_and_b32_e32 v5, 0xffff0000, v77
	v_mul_f32_e32 v5, v8, v5
	v_mul_f32_e32 v1, v8, v9
	v_mul_f32_e32 v9, v5, v75
	s_waitcnt lgkmcnt(1)
	v_lshlrev_b32_e32 v5, 16, v83
	v_mul_f32_e32 v5, v8, v5
	v_mul_f32_e32 v15, v5, v68
	v_and_b32_e32 v5, 0xffff0000, v83
	v_mul_f32_e32 v5, v8, v5
	v_mul_f32_e32 v2, v1, v2
	v_mul_f32_e32 v1, v8, v80
	v_mul_f32_e32 v67, v5, v69
	s_waitcnt lgkmcnt(0)
	v_lshlrev_b32_e32 v5, 16, v84
	v_mul_f32_e32 v66, v1, v3
	v_lshlrev_b32_e32 v1, 16, v76
	v_mul_f32_e32 v5, v8, v5
	v_mul_f32_e32 v1, v8, v1
	v_and_b32_e32 v3, 0xffff0000, v76
	v_mul_f32_e32 v68, v5, v70
	v_and_b32_e32 v5, 0xffff0000, v84
	v_mul_f32_e32 v1, v1, v72
	v_mul_f32_e32 v3, v8, v3
	v_mul_f32_e32 v5, v8, v5
	v_mul_f32_e32 v3, v3, v73
	v_mul_f32_e32 v8, v5, v71
	v_cndmask_b32_e64 v5, v1, -v1, vcc
	v_pk_mul_f32 v[4:5], v[50:51], v[4:5]
	v_cndmask_b32_e64 v11, v3, -v3, vcc
	v_add_f32_e32 v50, v4, v5
	v_pk_mul_f32 v[4:5], v[52:53], v[10:11]
	v_cndmask_b32_e64 v7, v7, -v7, vcc
	v_add_f32_e32 v10, v4, v5
	v_pk_mul_f32 v[4:5], v[54:55], v[6:7]
	v_cndmask_b32_e64 v13, v9, -v9, vcc
	v_cndmask_b32_e64 v1, v15, -v15, vcc
	v_add_f32_e32 v6, v4, v5
	v_pk_mul_f32 v[4:5], v[56:57], v[12:13]
	v_pk_mul_f32 v[0:1], v[58:59], v[0:1]
	v_cndmask_b32_e64 v15, v67, -v67, vcc
	v_add_f32_e32 v4, v4, v5
	v_add_f32_e32 v5, v0, v1
	v_pk_mul_f32 v[0:1], v[60:61], v[14:15]
	v_cndmask_b32_e64 v3, v68, -v68, vcc
	v_add_f32_e32 v7, v0, v1
	v_pk_mul_f32 v[0:1], v[62:63], v[2:3]
	v_cndmask_b32_e64 v67, v8, -v8, vcc
	v_add_f32_e32 v3, v0, v1
	v_pk_mul_f32 v[0:1], v[64:65], v[66:67]
	s_nop 0
	v_add_f32_e32 v8, v0, v1
	v_cvt_pk_bf16_f32 v0, v50, v10
	v_cvt_pk_bf16_f32 v1, v6, v4
	v_cvt_pk_bf16_f32 v2, v5, v7
	v_cvt_pk_bf16_f32 v3, v3, v8
	global_store_dwordx4 v[78:79], v[0:3], off offset:128
	s_andn2_b64 exec, exec, s[8:9]
	s_cbranch_execnz .LBB0_972
